# mixer-B loop: per-item persistent constants and LDS-DMA lane offsets (fewer VALU per tile)
# baseline (speedup 1.0000x reference)
; #define VSYNC() vb_sync(vc)
; template <int NS>
; DI void attn_item(const Params& p, int layer, char* smem, VBC& vc, int b, int hq, int qblk) {
;     ...
;     auto tile_ptrs = [&](int it, const u16*& kp, const u16*& vp) {
;         if (it < lat1 - lat0) { int kt = lat0 + it; kp = P + (size_t)(b * SEQ + kt * 64) * PC + kcol; vp = VT + kt * 64; }
;         else { int c = it - (lat1 - lat0); kp = P + (size_t)(NLAT + b * CTXL + c * 64) * PC + kcol; vp = VT + SEQ + c * 64; }
;     };
;     auto dma_tile = [&](int it, int st) {
;         const u16 *kp, *vp; tile_ptrs(it, kp, vp);
; #pragma unroll
;         for (int i = 0; i < 2; ++i) {
;             const int row = wave4 * 16 + i * 8 + drow;
;             const int chunk = dslot ^ ((row >> 1) & 7);
;             lds_u32* dk = (lds_u32*)(sK + st * 8192 + (wave4 * 16 + i * 8) * 64);
;             lds_u32* dv = (lds_u32*)(sK + st * 8192 + 4096 + (wave4 * 16 + i * 8) * 64);
;             __builtin_amdgcn_global_load_lds((const unsigned*)(kp + (size_t)row * PC + chunk * 8), dk, 16, 0, 0);
;             __builtin_amdgcn_global_load_lds((const unsigned*)(vp + (size_t)row * KVS + chunk * 8), dv, 16, 0, 0);
;         }
;     };
;     const int hs16 = ((h ^ ((r >> 1) & 7)) << 3);
;     const bf16x8 kones = __builtin_bit_cast(bf16x8, (uint4){0x00003F80u, 0u, 0u, 0u});
;     auto run_tiles = [&](const bool fast) {
;     dma_tile(0, 0);
;     asm volatile("s_waitcnt vmcnt(0)" ::: "memory");
;     VSYNC();
;     for (int it = 0; it < ntiles; ++it) {
;         const int buf = it & 1;
;         if (it + 1 < ntiles) dma_tile(it + 1, buf ^ 1);
;         const u16* cK = sK + buf * 8192; const u16* cV = cK + 4096;
;         const bool is_lat = it < lat1 - lat0;
;         const int kpos0 = (lat0 + it) * 64;
;         auto qk = [&](const int m, f32x16 (&s)[2]) {
; #pragma unroll
;             for (int kt2 = 0; kt2 < 2; ++kt2)
; #pragma unroll
;                 for (int e = 0; e < 16; ++e) s[kt2][e] = 0.f;
;             __builtin_amdgcn_s_setprio(1);
; #pragma unroll
;             for (int ks = 0; ks < NKS; ++ks)
; #pragma unroll
;                 for (int kt2 = 0; kt2 < 2; ++kt2) s[kt2] = MFMA(ld8(cK + (kt2 * 32 + r) * 64 + (((m * DQK + ks * 16)) ^ hs16)), qf[m][ks], s[kt2]);
; #pragma unroll
;             for (int kt2 = 0; kt2 < 2; ++kt2) { uint4 qa4 = {qaug[m], 0u, 0u, 0u}; s[kt2] = MFMA(kones, __builtin_bit_cast(bf16x8, qa4), s[kt2]); }
.Lr_takeover:
	v_readlane_b32 s0, v252, 21
	s_lshr_b32 s0, s0, 4
	s_add_i32 s0, s0, s33
	s_add_i32 s16, s0, 0x10000
	v_lshl_add_u32 v5, v241, 1, s33
	v_lshl_add_u32 v6, v243, 1, s33
	s_nop 0
	v_readfirstlane_b32 s98, v5
	v_readfirstlane_b32 s99, v6
	v_mov_b32_e32 v8, v192
	v_mov_b32_e32 v9, 0
	v_mov_b32_e32 v10, 0
	v_mov_b32_e32 v11, 0
	v_mov_b32_e32 v13, 0
	v_mov_b32_e32 v14, 0
	v_mov_b32_e32 v15, 0
	v_mov_b32_e32 v12, s52
	v_add_u32_e32 v254, v206, v222
	v_add_u32_e32 v255, v208, v222
	v_add_u32_e32 v193, v210, v224
	v_add_u32_e32 v195, v212, v224
	s_mov_b32 s47, 2
	s_mov_b32 s55, 0x8000
	s_cmp_lt_u32 s47, s21
	s_cselect_b64 s[0:1], -1, 0
	s_sub_i32 s17, s47, s21
	s_min_u32 s17, s47, s17
	s_and_b64 s[0:1], s[0:1], exec
	s_cselect_b32 s0, s20, s27
	s_cselect_b32 s1, s25, s41
	s_cselect_b32 s48, s24, s40
	s_lshl_b32 s49, s17, 6
	s_add_i32 s49, s49, s0
	s_lshl_b32 s0, s17, 7
	s_add_u32 s0, s48, s0
	s_addc_u32 s1, s1, 0
	s_mul_hi_i32 s17, s49, 0x1a80
	s_mulk_i32 s49, 0x1a80
	s_add_u32 s48, s42, s49
	s_addc_u32 s49, s43, s17
	v_add_u32_e32 v2, v206, v222
	s_add_i32 m0, s98, s55
	v_add_u32_e32 v3, v208, v222
	global_load_lds_dwordx4 v2, s[48:49]
	s_add_i32 m0, m0, 0x2000
	v_add_u32_e32 v5, v210, v224
	global_load_lds_dwordx4 v3, s[0:1]
	s_add_i32 m0, s99, s55
	v_add_u32_e32 v6, v212, v224
	global_load_lds_dwordx4 v5, s[48:49]
	s_add_i32 m0, m0, 0x2000
	s_nop 0
	global_load_lds_dwordx4 v6, s[0:1]
	s_mov_b32 s47, 3
	s_mov_b32 s55, 0xc000
	s_cmp_lt_u32 s47, s21
	s_cselect_b64 s[0:1], -1, 0
	s_sub_i32 s17, s47, s21
	s_min_u32 s17, s47, s17
	s_and_b64 s[0:1], s[0:1], exec
	s_cselect_b32 s0, s20, s27
	s_cselect_b32 s1, s25, s41
	s_cselect_b32 s48, s24, s40
	s_lshl_b32 s49, s17, 6
	s_add_i32 s49, s49, s0
	s_lshl_b32 s0, s17, 7
	s_add_u32 s0, s48, s0
	s_addc_u32 s1, s1, 0
	s_mul_hi_i32 s17, s49, 0x1a80
	s_mulk_i32 s49, 0x1a80
	s_add_u32 s48, s42, s49
	s_addc_u32 s49, s43, s17
	v_add_u32_e32 v2, v206, v222
	s_add_i32 m0, s98, s55
	v_add_u32_e32 v3, v208, v222
	global_load_lds_dwordx4 v2, s[48:49]
	s_add_i32 m0, m0, 0x2000
	v_add_u32_e32 v5, v210, v224
	global_load_lds_dwordx4 v3, s[0:1]
	s_add_i32 m0, s99, s55
	v_add_u32_e32 v6, v212, v224
	global_load_lds_dwordx4 v5, s[48:49]
	s_add_i32 m0, m0, 0x2000
	s_nop 0
	global_load_lds_dwordx4 v6, s[0:1]
	s_movk_i32 s17, 0x2000
.Lr_body:
	v_lshl_add_u32 v226, s17, 1, v248
	v_lshl_add_u32 v5, v201, 1, v226
	v_lshl_add_u32 v6, v245, 1, v226
	ds_read_b128 v[112:115], v5
	ds_read_b128 v[116:119], v5 offset:4096
	v_lshl_add_u32 v223, v246, 1, v226
	ds_read_b128 v[120:123], v6
	ds_read_b128 v[124:127], v6 offset:4096
	v_lshl_add_u32 v225, v247, 1, v226
	ds_read_b128 v[128:131], v223
	ds_read_b128 v[132:135], v223 offset:4096
	ds_read_b128 v[136:139], v225
	ds_read_b128 v[140:143], v225 offset:4096
	v_mov_b32_e32 v2, 0
	v_mov_b32_e32 v3, 0
	s_waitcnt lgkmcnt(7)
	v_mfma_f32_32x32x16_bf16 v[96:111], v[112:115], v[176:179], 0
	s_waitcnt lgkmcnt(6)
	v_mfma_f32_32x32x16_bf16 v[80:95], v[116:119], v[176:179], 0
	s_waitcnt lgkmcnt(5)
	v_mfma_f32_32x32x16_bf16 v[96:111], v[120:123], v[180:183], v[96:111]
	s_waitcnt lgkmcnt(4)
	v_mfma_f32_32x32x16_bf16 v[80:95], v[124:127], v[180:183], v[80:95]
	ds_read_b128 v[112:115], v5 offset:8192
	ds_read_b128 v[116:119], v5 offset:12288
	v_mfma_f32_32x32x16_bf16 v[96:111], v[12:15], v[0:3], v[96:111]
	ds_read_b128 v[120:123], v6 offset:8192
	ds_read_b128 v[124:127], v6 offset:12288
	v_mfma_f32_32x32x16_bf16 v[80:95], v[12:15], v[0:3], v[80:95]
	s_waitcnt lgkmcnt(7)
	v_mfma_f32_32x32x16_bf16 v[144:159], v[128:131], v[184:187], 0
	s_waitcnt lgkmcnt(6)
	v_mfma_f32_32x32x16_bf16 v[160:175], v[132:135], v[184:187], 0
	s_waitcnt lgkmcnt(5)
	v_mfma_f32_32x32x16_bf16 v[144:159], v[136:139], v[188:191], v[144:159]
	s_waitcnt lgkmcnt(4)
	v_mfma_f32_32x32x16_bf16 v[160:175], v[140:143], v[188:191], v[160:175]
	ds_read_b128 v[128:131], v223 offset:8192
	ds_read_b128 v[132:135], v223 offset:12288
	v_exp_f32_e32 v96, v96
	v_exp_f32_e32 v97, v97
	v_exp_f32_e32 v98, v98
	v_exp_f32_e32 v99, v99
	v_mfma_f32_32x32x16_bf16 v[144:159], v[12:15], v[8:11], v[144:159]
	ds_read_b128 v[136:139], v225 offset:8192
	ds_read_b128 v[140:143], v225 offset:12288
	v_exp_f32_e32 v100, v100
	v_exp_f32_e32 v101, v101
	v_pk_add_f32 v[2:3], v[96:97], v[98:99]
	v_exp_f32_e32 v102, v102
	v_exp_f32_e32 v103, v103
	v_pk_add_f32 v[2:3], v[2:3], v[100:101]
	v_mfma_f32_32x32x16_bf16 v[160:175], v[12:15], v[8:11], v[160:175]
	v_exp_f32_e32 v104, v104
	v_exp_f32_e32 v105, v105
	v_pk_add_f32 v[2:3], v[2:3], v[102:103]
	v_exp_f32_e32 v106, v106
	v_exp_f32_e32 v107, v107
	v_pk_add_f32 v[2:3], v[2:3], v[104:105]
	v_exp_f32_e32 v108, v108
	v_exp_f32_e32 v109, v109
	v_pk_add_f32 v[2:3], v[2:3], v[106:107]
	v_exp_f32_e32 v110, v110
	v_exp_f32_e32 v111, v111
	v_pk_add_f32 v[2:3], v[2:3], v[108:109]
	v_exp_f32_e32 v80, v80
	v_exp_f32_e32 v81, v81
	v_pk_add_f32 v[2:3], v[2:3], v[110:111]
	v_exp_f32_e32 v82, v82
	v_exp_f32_e32 v83, v83
	v_pk_add_f32 v[2:3], v[2:3], v[80:81]
	v_exp_f32_e32 v84, v84
	v_exp_f32_e32 v85, v85
	v_pk_add_f32 v[2:3], v[2:3], v[82:83]
	v_exp_f32_e32 v86, v86
	v_exp_f32_e32 v87, v87
	v_pk_add_f32 v[2:3], v[2:3], v[84:85]
	v_exp_f32_e32 v88, v88
	v_exp_f32_e32 v89, v89
	v_pk_add_f32 v[2:3], v[2:3], v[86:87]
	v_exp_f32_e32 v90, v90
	v_exp_f32_e32 v91, v91
	v_pk_add_f32 v[2:3], v[2:3], v[88:89]
	v_exp_f32_e32 v92, v92
	v_exp_f32_e32 v93, v93
	v_pk_add_f32 v[2:3], v[2:3], v[90:91]
	v_exp_f32_e32 v94, v94
	v_exp_f32_e32 v95, v95
	v_pk_add_f32 v[2:3], v[2:3], v[92:93]
	v_mov_b32_e32 v96, v96
	v_pk_add_f32 v[2:3], v[2:3], v[94:95]
	v_cvt_pk_bf16_f32 v96, v96, v97
	v_cvt_pk_bf16_f32 v97, v98, v99
	v_cvt_pk_bf16_f32 v98, v100, v101
	v_cvt_pk_bf16_f32 v99, v102, v103
	v_cvt_pk_bf16_f32 v100, v104, v105
	v_cvt_pk_bf16_f32 v101, v106, v107
	v_cvt_pk_bf16_f32 v102, v108, v109
	v_cvt_pk_bf16_f32 v103, v110, v111
	v_cvt_pk_bf16_f32 v80, v80, v81
	v_cvt_pk_bf16_f32 v81, v82, v83
	v_cvt_pk_bf16_f32 v82, v84, v85
	v_cvt_pk_bf16_f32 v83, v86, v87
	v_cvt_pk_bf16_f32 v84, v88, v89
	v_cvt_pk_bf16_f32 v85, v90, v91
	v_cvt_pk_bf16_f32 v86, v92, v93
	v_cvt_pk_bf16_f32 v87, v94, v95
	v_add_f32_e32 v2, v2, v3
	v_add_f32_e32 v194, v194, v2
	s_waitcnt lgkmcnt(7)
; DI u16 f2bf(float a) { return (u16)(pk2(a, 0.f) & 0xffffu); }
; template <int NS>
; DI void attn_item(const Params& p, int layer, char* smem, VBC& vc, int b, int hq, int qblk) {
;     ...
;             if (fixed) {
;                 float ls = 0.f;
; #pragma unroll
;                 for (int kt2 = 0; kt2 < 2; ++kt2)
; #pragma unroll
;                     for (int e = 0; e < 16; ++e) { const float pv = __builtin_amdgcn_exp2f(s[kt2][e]); s[kt2][e] = pv; ls += pv; }
;                 lrun[m] += ls;
;             } else {
;                 float tmax = -1e30f;
;     #pragma unroll
;                 for (int kt2 = 0; kt2 < 2; ++kt2)
;     #pragma unroll
;                     for (int e = 0; e < 16; ++e) tmax = fmaxf(tmax, s[kt2][e]);
;                 tmax = fmaxf(tmax, __shfl_xor(tmax, 32));
;                 float mnew = fmaxf(mrun[m], tmax * cexp);
;                 if (fast) mnew = bf2f(f2bf(mnew));
;                 const float alpha = __builtin_amdgcn_exp2f(mrun[m] - mnew);
;                 mrun[m] = mnew;
;                 f32x2 ls2 = {0.f, 0.f};
;                 const f32x2 cc2 = {cexp, cexp}, mm2 = {-mnew, -mnew};
;     #pragma unroll
;                 for (int kt2 = 0; kt2 < 2; ++kt2)
;     #pragma unroll
;                     for (int e = 0; e < 16; e += 2) {
;                         f32x2 sv = {s[kt2][e], s[kt2][e + 1]};
;                         sv = __builtin_elementwise_fma(sv, cc2, mm2);
;                         f32x2 pv = {__builtin_amdgcn_exp2f(sv.x), __builtin_amdgcn_exp2f(sv.y)};
;                         s[kt2][e] = pv.x; s[kt2][e + 1] = pv.y; ls2 += pv;
;                     }
;                 lrun[m] = lrun[m] * alpha + (ls2.x + ls2.y);
;                 if (__any(alpha != 1.f)) {
;     #pragma unroll
;                     for (int t = 0; t < 2; ++t)
;     #pragma unroll
;                         for (int e = 0; e < 16; ++e) O[m][t][e] *= alpha;
;                 }
;                 if (fast) {
;                     qaug[m] = h == 0 ? (unsigned)f2bf(-mrun[m]) : 0u;
;                 }
;             }
; #pragma unroll
;             for (int kt2 = 0; kt2 < 2; ++kt2) { pf[kt2][0] = pack8(s[kt2], 0); pf[kt2][1] = pack8(s[kt2], 1); }
;         };
;         auto pvm = [&](const int m, const bf16x8 (&pf)[2][2]) {
;             __builtin_amdgcn_s_setprio(1);
; #pragma unroll
;             for (int kk = 0; kk < 4; ++kk)
; #pragma unroll
	v_mfma_f32_32x32x16_bf16 v[64:79], v[112:115], v[96:99], v[64:79]
	v_exp_f32_e32 v144, v144
	v_exp_f32_e32 v145, v145
	v_exp_f32_e32 v146, v146
	v_exp_f32_e32 v147, v147
	v_exp_f32_e32 v148, v148
	v_exp_f32_e32 v149, v149
	v_pk_add_f32 v[92:93], v[144:145], v[146:147]
	v_exp_f32_e32 v150, v150
	s_waitcnt lgkmcnt(6)
	v_mfma_f32_32x32x16_bf16 v[32:47], v[116:119], v[96:99], v[32:47]
	v_exp_f32_e32 v151, v151
	v_pk_add_f32 v[92:93], v[92:93], v[148:149]
	v_exp_f32_e32 v152, v152
	v_exp_f32_e32 v153, v153
	v_pk_add_f32 v[92:93], v[92:93], v[150:151]
	v_exp_f32_e32 v154, v154
	v_exp_f32_e32 v155, v155
	v_pk_add_f32 v[92:93], v[92:93], v[152:153]
	s_waitcnt lgkmcnt(5)
	v_mfma_f32_32x32x16_bf16 v[64:79], v[120:123], v[100:103], v[64:79]
	v_exp_f32_e32 v156, v156
	v_exp_f32_e32 v157, v157
	v_pk_add_f32 v[92:93], v[92:93], v[154:155]
	v_exp_f32_e32 v158, v158
	v_exp_f32_e32 v159, v159
	v_pk_add_f32 v[92:93], v[92:93], v[156:157]
	v_exp_f32_e32 v160, v160
	v_exp_f32_e32 v161, v161
	s_waitcnt lgkmcnt(4)
	v_mfma_f32_32x32x16_bf16 v[32:47], v[124:127], v[100:103], v[32:47]
	v_pk_add_f32 v[92:93], v[92:93], v[158:159]
	v_exp_f32_e32 v162, v162
	v_exp_f32_e32 v163, v163
	v_pk_add_f32 v[92:93], v[92:93], v[160:161]
	v_exp_f32_e32 v164, v164
	v_exp_f32_e32 v165, v165
	v_pk_add_f32 v[92:93], v[92:93], v[162:163]
	v_exp_f32_e32 v166, v166
	s_waitcnt lgkmcnt(3)
	v_mfma_f32_32x32x16_bf16 v[64:79], v[128:131], v[80:83], v[64:79]
	v_exp_f32_e32 v167, v167
	v_pk_add_f32 v[92:93], v[92:93], v[164:165]
	v_exp_f32_e32 v168, v168
	v_exp_f32_e32 v169, v169
	v_pk_add_f32 v[92:93], v[92:93], v[166:167]
	v_exp_f32_e32 v170, v170
	v_exp_f32_e32 v171, v171
	v_pk_add_f32 v[92:93], v[92:93], v[168:169]
	s_waitcnt lgkmcnt(2)
	v_mfma_f32_32x32x16_bf16 v[32:47], v[132:135], v[80:83], v[32:47]
	v_exp_f32_e32 v172, v172
	v_exp_f32_e32 v173, v173
	v_pk_add_f32 v[92:93], v[92:93], v[170:171]
	v_exp_f32_e32 v174, v174
	v_exp_f32_e32 v175, v175
	v_pk_add_f32 v[92:93], v[92:93], v[172:173]
	v_mov_b32_e32 v144, v144
	v_pk_add_f32 v[92:93], v[92:93], v[174:175]
	s_waitcnt lgkmcnt(1)
	v_mfma_f32_32x32x16_bf16 v[64:79], v[136:139], v[84:87], v[64:79]
	s_waitcnt lgkmcnt(0)
	v_mfma_f32_32x32x16_bf16 v[32:47], v[140:143], v[84:87], v[32:47]
	v_cvt_pk_bf16_f32 v144, v144, v145
	v_cvt_pk_bf16_f32 v145, v146, v147
	v_cvt_pk_bf16_f32 v146, v148, v149
	v_cvt_pk_bf16_f32 v147, v150, v151
	v_cvt_pk_bf16_f32 v148, v152, v153
	v_cvt_pk_bf16_f32 v149, v154, v155
	v_cvt_pk_bf16_f32 v150, v156, v157
	v_cvt_pk_bf16_f32 v151, v158, v159
	v_cvt_pk_bf16_f32 v160, v160, v161
	v_cvt_pk_bf16_f32 v161, v162, v163
	v_cvt_pk_bf16_f32 v162, v164, v165
	v_cvt_pk_bf16_f32 v163, v166, v167
	v_cvt_pk_bf16_f32 v164, v168, v169
	v_cvt_pk_bf16_f32 v165, v170, v171
	v_cvt_pk_bf16_f32 v166, v172, v173
	v_cvt_pk_bf16_f32 v167, v174, v175
	v_add_f32_e32 v92, v92, v93
	v_add_f32_e32 v4, v4, v92
	s_nop 1
	s_cmp_lg_u32 s46, s44
	s_cbranch_scc0 .Lr_last
	v_mfma_f32_32x32x16_bf16 v[48:63], v[112:115], v[144:147], v[48:63]
	s_waitcnt vmcnt(0)
	v_mov_b32_e32 v2, s16
	v_mov_b32_e32 v3, s46
	s_mov_b64 exec, 1
	ds_write_b32 v2, v3
	s_mov_b64 exec, -1
	s_add_i32 s0, s33, 0x10000
	v_mov_b32_e32 v6, s0
	ds_read_b128 v[88:91], v6
	v_mfma_f32_32x32x16_bf16 v[16:31], v[116:119], v[144:147], v[16:31]
	s_add_i32 s54, s46, -1
	s_max_i32 s54, s54, 1
	s_add_i32 s47, s46, 3
	s_and_b32 s55, s47, 3
	s_lshl_b32 s55, s55, 14
	s_cmp_lt_u32 s47, s21
	s_cselect_b64 s[0:1], -1, 0
	s_sub_i32 s17, s47, s21
	s_min_u32 s17, s47, s17
	s_and_b64 s[0:1], s[0:1], exec
	s_cselect_b32 s0, s20, s27
	s_cselect_b32 s1, s25, s41
	s_cselect_b32 s48, s24, s40
	s_lshl_b32 s49, s17, 6
	s_add_i32 s49, s49, s0
	s_lshl_b32 s0, s17, 7
	s_add_u32 s0, s48, s0
	s_addc_u32 s1, s1, 0
	s_mul_hi_i32 s17, s49, 0x1a80
	s_mulk_i32 s49, 0x1a80
	s_add_u32 s48, s42, s49
	s_addc_u32 s49, s43, s17
	v_mfma_f32_32x32x16_bf16 v[48:63], v[120:123], v[148:151], v[48:63]
	s_waitcnt lgkmcnt(0)
	v_min3_u32 v88, v88, v89, v90
	v_min_u32_e32 v88, v88, v91
	v_mfma_f32_32x32x16_bf16 v[16:31], v[124:127], v[148:151], v[16:31]
	v_cmp_gt_u32_e32 vcc, s54, v88
	s_cbranch_vccnz .Lr_pollslow
.Lr_ready:
	s_cmp_lt_u32 s47, s26
	s_cbranch_scc0 .Lr_nodma
	s_add_i32 m0, s98, s55
	s_nop 0
	global_load_lds_dwordx4 v254, s[48:49]
	v_mfma_f32_32x32x16_bf16 v[48:63], v[128:131], v[160:163], v[48:63]
	s_add_i32 m0, m0, 0x2000
	s_nop 0
	global_load_lds_dwordx4 v255, s[0:1]
	v_mfma_f32_32x32x16_bf16 v[16:31], v[132:135], v[160:163], v[16:31]
	s_add_i32 m0, s99, s55
	s_nop 0
	global_load_lds_dwordx4 v193, s[48:49]
	v_mfma_f32_32x32x16_bf16 v[48:63], v[136:139], v[164:167], v[48:63]
	s_add_i32 m0, m0, 0x2000
	s_nop 0
	global_load_lds_dwordx4 v195, s[0:1]
	v_mfma_f32_32x32x16_bf16 v[16:31], v[140:143], v[164:167], v[16:31]
	s_branch .Lr_next

; #define VSYNC() vb_sync(vc)
; template <int NS>
; DI void attn_item(const Params& p, int layer, char* smem, VBC& vc, int b, int hq, int qblk) {
;     ...
;         asm volatile("s_waitcnt vmcnt(0)" ::: "memory");
;         VSYNC();
.Lr_pollslow:
	s_sleep 1
	v_mov_b32_e32 v6, s33
	v_add_u32_e32 v6, 0x10000, v6
	ds_read_b128 v[88:91], v6
	s_waitcnt lgkmcnt(0)
	v_min3_u32 v88, v88, v89, v90
	v_min_u32_e32 v88, v88, v91
	v_cmp_gt_u32_e32 vcc, s54, v88
	s_cbranch_vccnz .Lr_pollslow
	s_branch .Lr_ready

; __global__ void __launch_bounds__(512, 2) hybrid_fwd(Params p, int lo, int hi) {
;     extern __shared__ __attribute__((aligned(16))) unsigned char dyn_lds[];
;     const int wid = __builtin_amdgcn_readfirstlane((int)(threadIdx.x >> 6));
	.amdhsa_kernel _Z10hybrid_fwd6Paramsii
		.amdhsa_group_segment_fixed_size 0
		.amdhsa_private_segment_fixed_size 0
		.amdhsa_kernarg_size 408
		.amdhsa_user_sgpr_count 2
		.amdhsa_user_sgpr_dispatch_ptr 0
		.amdhsa_user_sgpr_queue_ptr 0
		.amdhsa_user_sgpr_kernarg_segment_ptr 1
		.amdhsa_user_sgpr_dispatch_id 0
		.amdhsa_user_sgpr_kernarg_preload_length 0
		.amdhsa_user_sgpr_kernarg_preload_offset 0
		.amdhsa_user_sgpr_private_segment_size 0
		.amdhsa_uses_dynamic_stack 0
		.amdhsa_enable_private_segment 0
		.amdhsa_system_sgpr_workgroup_id_x 1
		.amdhsa_system_sgpr_workgroup_id_y 0
		.amdhsa_system_sgpr_workgroup_id_z 0
		.amdhsa_system_sgpr_workgroup_info 0
		.amdhsa_system_vgpr_workitem_id 2
		.amdhsa_next_free_vgpr 256
		.amdhsa_next_free_sgpr 102
		.amdhsa_accum_offset 256
		.amdhsa_reserve_vcc 1
		.amdhsa_float_round_mode_32 0
		.amdhsa_float_round_mode_16_64 0
		.amdhsa_float_denorm_mode_32 3
		.amdhsa_float_denorm_mode_16_64 3
		.amdhsa_dx10_clamp 1
		.amdhsa_ieee_mode 1
		.amdhsa_fp16_overflow 0
		.amdhsa_tg_split 0
		.amdhsa_exception_fp_ieee_invalid_op 0
		.amdhsa_exception_fp_denorm_src 0
		.amdhsa_exception_fp_ieee_div_zero 0
		.amdhsa_exception_fp_ieee_overflow 0
		.amdhsa_exception_fp_ieee_underflow 0
		.amdhsa_exception_fp_ieee_inexact 0
		.amdhsa_exception_int_div_zero 0
	.end_amdhsa_kernel

; __global__ void __launch_bounds__(512, 2) hybrid_fwd(Params p, int lo, int hi) {
;     extern __shared__ __attribute__((aligned(16))) unsigned char dyn_lds[];
;     const int wid = __builtin_amdgcn_readfirstlane((int)(threadIdx.x >> 6));
amdhsa.kernels:
  - .agpr_count:     0
    .args:
      - .offset:         0
        .size:           144
        .value_kind:     by_value
      - .offset:         144
        .size:           4
        .value_kind:     by_value
      - .offset:         148
        .size:           4
        .value_kind:     by_value
      - .offset:         152
        .size:           4
        .value_kind:     hidden_block_count_x
      - .offset:         156
        .size:           4
        .value_kind:     hidden_block_count_y
      - .offset:         160
        .size:           4
        .value_kind:     hidden_block_count_z
      - .offset:         164
        .size:           2
        .value_kind:     hidden_group_size_x
      - .offset:         166
        .size:           2
        .value_kind:     hidden_group_size_y
      - .offset:         168
        .size:           2
        .value_kind:     hidden_group_size_z
      - .offset:         170
        .size:           2
        .value_kind:     hidden_remainder_x
      - .offset:         172
        .size:           2
        .value_kind:     hidden_remainder_y
      - .offset:         174
        .size:           2
        .value_kind:     hidden_remainder_z
      - .offset:         192
        .size:           8
        .value_kind:     hidden_global_offset_x
      - .offset:         200
        .size:           8
        .value_kind:     hidden_global_offset_y
      - .offset:         208
        .size:           8
        .value_kind:     hidden_global_offset_z
      - .offset:         216
        .size:           2
        .value_kind:     hidden_grid_dims
      - .offset:         240
        .size:           8
        .value_kind:     hidden_multigrid_sync_arg
      - .offset:         272
        .size:           4
        .value_kind:     hidden_dynamic_lds_size
    .group_segment_fixed_size: 0
    .kernarg_segment_align: 8
    .kernarg_segment_size: 408
    .language:       OpenCL C
    .language_version:
      - 2
      - 0
    .max_flat_workgroup_size: 512
    .name:           _Z10hybrid_fwd6Paramsii
    .private_segment_fixed_size: 0
    .sgpr_count:     108
    .sgpr_spill_count: 224
    .symbol:         _Z10hybrid_fwd6Paramsii.kd
    .uniform_work_group_size: 1
    .uses_dynamic_stack: false
    .vgpr_count:     256
    .vgpr_spill_count: 0
    .wavefront_size: 64
